# GLU units shared by two workgroups + weight transposes in two passes: ff_w1 on the GLU phase's 64 idle workgroups, ff_w2 on the same workgroups during out_proj
# speedup vs baseline: 1.0147x; 1.0127x over previous
.Lp7_tr:
	s_mov_b64 s[16:17], s[0:1]
	s_load_dwordx2 s[18:19], s[0:1], 0xe8
	s_add_i32 s28, s2, 0x40
	s_movk_i32 s45, 0x40
	s_movk_i32 s32, 0x1ff
	s_branch .Lp6_common
.Lp6_tr:
	s_mov_b64 s[16:17], s[0:1]
	s_load_dwordx2 s[18:19], s[0:1], 0xe8
	s_sub_i32 s28, s2, 0xc0
	s_movk_i32 s45, 0x40
	s_movk_i32 s32, 0xff
.Lp6_common:
	s_waitcnt lgkmcnt(0)
	s_add_u32 s20, s18, 0x7bc000
	s_addc_u32 s21, s19, 0
	v_mov_b32_e32 v0, v170
	s_cmpk_gt_i32 s28, 0x1ff
	s_cbranch_scc1 .Lp6_ret
	v_add_u32_e32 v3, 0x200, v0
	v_ashrrev_i32_e32 v5, 6, v3
	v_add_u32_e32 v3, 0x400, v0
	v_ashrrev_i32_e32 v6, 6, v3
	v_add_u32_e32 v3, 0x600, v0
	v_ashrrev_i32_e32 v7, 6, v3
	v_add_u32_e32 v3, 0x800, v0
	v_ashrrev_i32_e32 v8, 6, v3
	v_add_u32_e32 v3, 0xa00, v0
	s_add_u32 s4, s18, 0x1ebc000
	v_ashrrev_i32_e32 v9, 6, v3
	v_add_u32_e32 v3, 0xc00, v0
	s_addc_u32 s5, s19, 0
	v_ashrrev_i32_e32 v10, 6, v3
	v_add_u32_e32 v3, 0xe00, v0
	s_add_u32 s29, s18, 0xebc000
	v_ashrrev_i32_e32 v11, 6, v3
	v_bfe_u32 v3, v0, 4, 2
	v_lshlrev_b32_e32 v12, 4, v0
	s_addc_u32 s30, s19, 0
	v_mul_u32_u24_e32 v3, 0x4100, v3
	v_and_b32_e32 v12, 0xf0, v12
	s_add_u32 s31, s18, 0xe3c000
	v_lshlrev_b32_e32 v1, 2, v0
	v_ashrrev_i32_e32 v4, 6, v0
	v_add3_u32 v3, 0, v3, v12
	v_ashrrev_i32_e32 v12, 3, v0
	v_lshlrev_b32_e32 v0, 3, v0
	s_addc_u32 s35, s19, 0
	v_and_b32_e32 v24, 56, v0
	s_add_u32 s6, s18, 0xdbc000
	v_mul_u32_u24_e32 v0, 0x41, v24
	s_addc_u32 s7, s19, 0
	s_movk_i32 s10, 0x104
	v_lshlrev_b32_e32 v14, 2, v12
	v_lshlrev_b32_e32 v0, 2, v0
	s_add_u32 s8, s18, 0xbbc000
	v_and_b32_e32 v2, 0xfc, v1
	v_mov_b32_e32 v1, 0
	v_mul_lo_u32 v15, v4, s10
	v_mul_lo_u32 v16, v5, s10
	v_mul_lo_u32 v17, v6, s10
	v_mul_lo_u32 v18, v7, s10
	v_mul_lo_u32 v19, v8, s10
	v_mul_lo_u32 v20, v9, s10
	v_mul_lo_u32 v21, v10, s10
	v_mul_lo_u32 v22, v11, s10
	v_add3_u32 v13, 0, v14, v0
	v_add3_u32 v14, 0, v0, v14
	s_addc_u32 s9, s19, 0
	s_mov_b32 s11, 0
	s_movk_i32 s36, 0xe0
	v_lshlrev_b32_e32 v0, 2, v2
	v_add_u32_e32 v15, v3, v15
	v_add_u32_e32 v16, v3, v16
	v_add_u32_e32 v17, v3, v17
	v_add_u32_e32 v18, v3, v18
	v_add_u32_e32 v19, v3, v19
	v_add_u32_e32 v20, v3, v20
	v_add_u32_e32 v21, v3, v21
	v_add_u32_e32 v22, v3, v22
	v_lshlrev_b32_e32 v2, 1, v24
	v_mov_b32_e32 v3, v1
	v_add_u32_e32 v23, 0x400, v13
	v_add_u32_e32 v24, 0x400, v14
	v_add_u32_e32 v25, 0x4000, v13
	v_add_u32_e32 v26, 0x4200, v14
	v_add_u32_e32 v27, 0x4400, v13
	v_add_u32_e32 v28, 0x4600, v14
	v_add_u32_e32 v29, 0x8200, v13
	v_add_u32_e32 v30, 0x8200, v14
	v_add_u32_e32 v31, 0x8600, v13
	v_add_u32_e32 v32, 0x8600, v14
	v_add_u32_e32 v33, 0xc200, v13
	v_add_u32_e32 v34, 0xc400, v14
	v_add_u32_e32 v35, 0xc600, v13
	v_add_u32_e32 v36, 0xc800, v14
	s_mov_b32 s37, s28
	s_branch .LBB0_804
.LBB0_803:
	s_lshr_b32 s24, s10, 8
	v_cvt_f32_u32_e32 v37, s24
	s_sub_i32 s33, 0, s24
	s_abs_i32 s26, s27
	s_ashr_i32 s25, s27, 31
	v_rcp_iflag_f32_e32 v37, v37
	s_nop 0
	v_mul_f32_e32 v37, 0x4f7ffffe, v37
	v_cvt_u32_f32_e32 v37, v37
	s_nop 0
	v_readfirstlane_b32 s40, v37
	s_mul_i32 s33, s33, s40
	s_mul_hi_u32 s33, s40, s33
	s_add_i32 s40, s40, s33
	s_mul_hi_u32 s33, s26, s40
	s_mul_i32 s40, s33, s24
	s_sub_i32 s26, s26, s40
	s_add_i32 s41, s33, 1
	s_sub_i32 s40, s26, s24
	s_cmp_ge_u32 s26, s24
	s_cselect_b32 s33, s41, s33
	s_cselect_b32 s26, s40, s26
	s_add_i32 s40, s33, 1
	s_cmp_ge_u32 s26, s24
	s_cselect_b32 s26, s40, s33
	s_xor_b32 s26, s26, s25
	s_sub_i32 s25, s26, s25
	s_mul_i32 s26, s25, s24
	s_lshl_b32 s24, s25, 6
	s_sub_i32 s25, s27, s26
	s_lshl_b32 s26, s25, 8
	s_ashr_i32 s27, s26, 31
	s_lshl_b64 s[40:41], s[26:27], 2
	s_waitcnt lgkmcnt(0)
	s_add_u32 s22, s22, s40
	v_add_u32_e32 v37, s24, v4
	s_addc_u32 s23, s23, s41
	v_lshl_add_u64 v[66:67], s[22:23], 0, v[0:1]
	v_mad_u64_u32 v[38:39], s[22:23], v37, s10, 0
	v_ashrrev_i32_e32 v41, 31, v37
	v_mov_b32_e32 v40, v39
	v_mad_u64_u32 v[40:41], s[22:23], v41, s10, v[40:41]
	v_mov_b32_e32 v39, v40
	v_add_u32_e32 v37, s24, v5
	v_lshl_add_u64 v[46:47], v[38:39], 2, v[66:67]
	v_mad_u64_u32 v[38:39], s[22:23], v37, s10, 0
	v_ashrrev_i32_e32 v41, 31, v37
	v_mov_b32_e32 v40, v39
	v_mad_u64_u32 v[40:41], s[22:23], v41, s10, v[40:41]
	v_mov_b32_e32 v39, v40
	v_add_u32_e32 v37, s24, v6
	v_lshl_add_u64 v[48:49], v[38:39], 2, v[66:67]
	global_load_dwordx4 v[38:41], v[46:47], off nt
	global_load_dwordx4 v[42:45], v[48:49], off nt
	v_mad_u64_u32 v[46:47], s[22:23], v37, s10, 0
	v_ashrrev_i32_e32 v49, 31, v37
	v_mov_b32_e32 v48, v47
	v_mad_u64_u32 v[48:49], s[22:23], v49, s10, v[48:49]
	v_mov_b32_e32 v47, v48
	v_add_u32_e32 v37, s24, v7
	v_lshl_add_u64 v[54:55], v[46:47], 2, v[66:67]
	v_mad_u64_u32 v[46:47], s[22:23], v37, s10, 0
	v_ashrrev_i32_e32 v49, 31, v37
	v_mov_b32_e32 v48, v47
	v_mad_u64_u32 v[48:49], s[22:23], v49, s10, v[48:49]
	v_mov_b32_e32 v47, v48
	v_add_u32_e32 v37, s24, v8
	v_lshl_add_u64 v[56:57], v[46:47], 2, v[66:67]
	global_load_dwordx4 v[46:49], v[54:55], off nt
	global_load_dwordx4 v[50:53], v[56:57], off nt
	v_mad_u64_u32 v[54:55], s[22:23], v37, s10, 0
	v_ashrrev_i32_e32 v57, 31, v37
	v_mov_b32_e32 v56, v55
	v_mad_u64_u32 v[56:57], s[22:23], v57, s10, v[56:57]
	v_mov_b32_e32 v55, v56
	v_add_u32_e32 v37, s24, v9
	v_lshl_add_u64 v[62:63], v[54:55], 2, v[66:67]
	v_mad_u64_u32 v[54:55], s[22:23], v37, s10, 0
	v_ashrrev_i32_e32 v57, 31, v37
	v_mov_b32_e32 v56, v55
	v_mad_u64_u32 v[56:57], s[22:23], v57, s10, v[56:57]
	v_mov_b32_e32 v55, v56
	v_lshl_add_u64 v[64:65], v[54:55], 2, v[66:67]
	global_load_dwordx4 v[54:57], v[62:63], off nt
	global_load_dwordx4 v[58:61], v[64:65], off nt
	v_add_u32_e32 v37, s24, v10
	v_mad_u64_u32 v[62:63], s[22:23], v37, s10, 0
	v_ashrrev_i32_e32 v65, 31, v37
	v_mov_b32_e32 v64, v63
	v_add_u32_e32 v37, s24, v11
	v_mad_u64_u32 v[64:65], s[22:23], v65, s10, v[64:65]
	v_mad_u64_u32 v[68:69], s[22:23], v37, s10, 0
	v_mov_b32_e32 v63, v64
	v_ashrrev_i32_e32 v71, 31, v37
	v_mov_b32_e32 v70, v69
	v_lshl_add_u64 v[62:63], v[62:63], 2, v[66:67]
	v_mad_u64_u32 v[70:71], s[22:23], v71, s10, v[70:71]
	global_load_dwordx4 v[62:65], v[62:63], off nt
	v_mov_b32_e32 v69, v70
	v_lshl_add_u64 v[66:67], v[68:69], 2, v[66:67]
	global_load_dwordx4 v[66:69], v[66:67], off nt
	s_waitcnt vmcnt(0)
	s_barrier
	s_ashr_i32 s25, s24, 31
	s_lshl_b64 s[22:23], s[24:25], 1
	v_add_u32_e32 v37, s26, v12
	s_add_u32 s14, s14, s22
	s_addc_u32 s15, s15, s23
	s_add_i32 s37, s37, s45
	s_cmp_gt_i32 s37, s32
	ds_write2_b32 v15, v38, v39 offset1:1
	ds_write2_b32 v15, v40, v41 offset0:2 offset1:3
	ds_write2_b32 v16, v42, v43 offset1:1
	ds_write2_b32 v16, v44, v45 offset0:2 offset1:3
	ds_write2_b32 v17, v46, v47 offset1:1
	ds_write2_b32 v17, v48, v49 offset0:2 offset1:3
	ds_write2_b32 v18, v50, v51 offset1:1
	ds_write2_b32 v18, v52, v53 offset0:2 offset1:3
	ds_write2_b32 v19, v54, v55 offset1:1
	ds_write2_b32 v19, v56, v57 offset0:2 offset1:3
	ds_write2_b32 v20, v58, v59 offset1:1
	ds_write2_b32 v20, v60, v61 offset0:2 offset1:3
	ds_write2_b32 v21, v62, v63 offset1:1
	ds_write2_b32 v21, v64, v65 offset0:2 offset1:3
	ds_write2_b32 v22, v66, v67 offset1:1
	ds_write2_b32 v22, v68, v69 offset0:2 offset1:3
	s_waitcnt lgkmcnt(0)
	s_barrier
	ds_read2_b32 v[38:39], v13 offset1:130
	ds_read2_b32 v[40:41], v14 offset0:65 offset1:195
	ds_read2_b32 v[42:43], v23 offset0:4 offset1:134
	ds_read2_b32 v[44:45], v24 offset0:69 offset1:199
	v_lshl_add_u64 v[46:47], s[14:15], 0, v[2:3]
	s_waitcnt lgkmcnt(2)
	v_cvt_pk_bf16_f32 v38, v38, v40
	v_cvt_pk_bf16_f32 v39, v39, v41
	s_waitcnt lgkmcnt(0)
	v_cvt_pk_bf16_f32 v40, v42, v44
	v_ashrrev_i32_e32 v42, 31, v37
	v_cvt_pk_bf16_f32 v41, v43, v45
	v_mul_lo_u32 v44, s12, v42
	v_mul_lo_u32 v45, s13, v37
	v_mad_u64_u32 v[42:43], s[14:15], s12, v37, 0
	v_add3_u32 v43, v43, v44, v45
	ds_read2_b32 v[44:45], v25 offset0:64 offset1:194
	ds_read2_b32 v[48:49], v26 offset0:1 offset1:131
	ds_read2_b32 v[50:51], v27 offset0:68 offset1:198
	ds_read2_b32 v[52:53], v28 offset0:5 offset1:135
	v_lshl_add_u64 v[42:43], v[42:43], 1, v[46:47]
	global_store_dwordx4 v[42:43], v[38:41], off
	v_add_u32_e32 v42, 64, v37
	v_ashrrev_i32_e32 v43, 31, v42
	s_waitcnt lgkmcnt(2)
	v_cvt_pk_bf16_f32 v38, v44, v48
	v_cvt_pk_bf16_f32 v39, v45, v49
	v_mul_lo_u32 v44, s12, v43
	v_mul_lo_u32 v45, s13, v42
	v_mad_u64_u32 v[42:43], s[14:15], s12, v42, 0
	s_waitcnt lgkmcnt(0)
	v_cvt_pk_bf16_f32 v40, v50, v52
	v_cvt_pk_bf16_f32 v41, v51, v53
	v_add3_u32 v43, v43, v44, v45
	ds_read2_b32 v[44:45], v29 offset1:130
	ds_read2_b32 v[48:49], v30 offset0:65 offset1:195
	ds_read2_b32 v[50:51], v31 offset0:4 offset1:134
	ds_read2_b32 v[52:53], v32 offset0:69 offset1:199
	v_lshl_add_u64 v[42:43], v[42:43], 1, v[46:47]
	global_store_dwordx4 v[42:43], v[38:41], off
	v_add_u32_e32 v42, 0x80, v37
	v_ashrrev_i32_e32 v43, 31, v42
	s_waitcnt lgkmcnt(2)
	v_cvt_pk_bf16_f32 v38, v44, v48
	v_cvt_pk_bf16_f32 v39, v45, v49
	v_mul_lo_u32 v44, s12, v43
	v_mul_lo_u32 v45, s13, v42
	v_mad_u64_u32 v[42:43], s[14:15], s12, v42, 0
	s_waitcnt lgkmcnt(0)
	v_cvt_pk_bf16_f32 v40, v50, v52
	v_cvt_pk_bf16_f32 v41, v51, v53
	v_add3_u32 v43, v43, v44, v45
	ds_read2_b32 v[44:45], v33 offset0:64 offset1:194
	ds_read2_b32 v[48:49], v34 offset0:1 offset1:131
	ds_read2_b32 v[50:51], v35 offset0:68 offset1:198
	ds_read2_b32 v[52:53], v36 offset0:5 offset1:135
	v_lshl_add_u64 v[42:43], v[42:43], 1, v[46:47]
	v_add_u32_e32 v37, 0xc0, v37
	global_store_dwordx4 v[42:43], v[38:41], off
	v_ashrrev_i32_e32 v42, 31, v37
	s_waitcnt lgkmcnt(2)
	v_cvt_pk_bf16_f32 v38, v44, v48
	v_cvt_pk_bf16_f32 v39, v45, v49
	v_mul_lo_u32 v44, s12, v42
	v_mul_lo_u32 v45, s13, v37
	v_mad_u64_u32 v[42:43], s[12:13], s12, v37, 0
	v_add3_u32 v43, v43, v44, v45
	s_waitcnt lgkmcnt(0)
	v_cvt_pk_bf16_f32 v40, v50, v52
	v_cvt_pk_bf16_f32 v41, v51, v53
	v_lshl_add_u64 v[42:43], v[42:43], 1, v[46:47]
	global_store_dwordx4 v[42:43], v[38:41], off
	s_cbranch_scc1 .Lp6_ret

.Lp6_ret:
	s_mov_b64 exec, -1
	s_cmpk_eq_i32 s32, 0xff
	s_cbranch_scc1 .LBB0_1182
	s_mov_b64 s[14:15], 0
	s_branch .LBB0_1246
